# phase-3 attention: gate block loaded coalesced (3 dwordx4 + 2 dwordx2) and transposed through wave-private LDS in the epilogue instead of 8 row-per-lane loads
# speedup vs baseline: 1.0056x; 1.0056x over previous
.LBB0_759:
	s_or_b64 exec, exec, s[14:15]
	v_lshrrev_b32_e32 v216, 6, v140
	v_mul_u32_u24_e32 v216, 0x1200, v216
	v_add_u32_e32 v216, v216, v141
	v_add_u32_e32 v216, 0x3000, v216
	v_lshrrev_b32_e32 v220, 3, v198
	v_and_b32_e32 v221, 7, v198
	v_mul_u32_u24_e32 v217, 0x90, v220
	v_lshl_add_u32 v217, v221, 4, v217
	v_add_u32_e32 v217, v217, v216
	v_lshrrev_b32_e32 v220, 4, v198
	v_and_b32_e32 v221, 15, v198
	v_mul_u32_u24_e32 v222, 0x90, v220
	v_lshl_add_u32 v222, v221, 3, v222
	v_add_u32_e32 v222, v222, v216
	v_and_b32_e32 v218, 31, v198
	v_lshrrev_b32_e32 v219, 5, v198
	v_mul_u32_u24_e32 v223, 0x90, v218
	v_lshl_add_u32 v223, v219, 3, v223
	v_add_u32_e32 v216, v223, v216
	ds_write_b128 v217, v[112:115]
	ds_write_b128 v217, v[116:119] offset:1152
	ds_write_b128 v217, v[120:123] offset:2304
	ds_write_b64 v222, v[124:125] offset:3456
	ds_write_b64 v222, v[128:129] offset:4032
	s_waitcnt lgkmcnt(0)
	ds_read_b64 v[128:129], v216
	ds_read_b64 v[124:125], v216 offset:16
	ds_read_b64 v[122:123], v216 offset:32
	ds_read_b64 v[120:121], v216 offset:48
	ds_read_b64 v[118:119], v216 offset:64
	ds_read_b64 v[116:117], v216 offset:80
	ds_read_b64 v[114:115], v216 offset:96
	ds_read_b64 v[112:113], v216 offset:112
	s_waitcnt lgkmcnt(0)
	ds_bpermute_b32 v4, v234, v10
	v_and_b32_e32 v5, 0xffff0000, v128
	v_lshl_add_u64 v[2:3], v[126:127], 1, v[130:131]
	v_lshl_add_u64 v[2:3], v[2:3], 0, v[0:1]
	s_waitcnt lgkmcnt(0)
	v_add_f32_e32 v4, v10, v4
	v_max_f32_e32 v6, 0xda24260, v4
	v_div_scale_f32 v7, s[14:15], v6, v6, 1.0
	v_rcp_f32_e32 v8, v7
	v_div_scale_f32 v9, vcc, 1.0, v6, 1.0
	v_lshlrev_b32_e32 v4, 16, v128
	v_fma_f32 v10, -v7, v8, 1.0
	v_fmac_f32_e32 v8, v10, v8
	v_mul_f32_e32 v10, v9, v8
	v_fma_f32 v11, -v7, v10, v9
	v_fmac_f32_e32 v10, v11, v8
	v_fma_f32 v7, -v7, v10, v9
	v_div_fmas_f32 v7, v7, v8, v10
	v_div_fixup_f32 v6, v7, v6, 1.0
	v_pk_mul_f32 v[8:9], v[32:33], v[6:7] op_sel_hi:[1,0]
	v_pk_mul_f32 v[10:11], v[34:35], v[6:7] op_sel_hi:[1,0]
	v_pk_mul_f32 v[4:5], v[8:9], v[4:5]
	v_and_b32_e32 v9, 0xffff0000, v129
	v_lshlrev_b32_e32 v8, 16, v129
	v_pk_mul_f32 v[8:9], v[10:11], v[8:9]
	s_mov_b64 s[14:15], 0x16f80400
	v_cvt_pk_bf16_f32 v4, v4, v5
	v_cvt_pk_bf16_f32 v5, v8, v9
	v_lshl_add_u64 v[8:9], v[2:3], 0, s[14:15]
	s_mov_b32 s14, 0x16f80000
	v_add_co_u32_e32 v2, vcc, s14, v2
	v_pk_mul_f32 v[10:11], v[38:39], v[6:7] op_sel_hi:[1,0]
	s_nop 0
	v_addc_co_u32_e32 v3, vcc, 0, v3, vcc
	v_lshrrev_b32_e32 v216, 6, v140
	v_mul_u32_u24_e32 v216, 0x1200, v216
	v_add_u32_e32 v216, v216, v141
	v_add_u32_e32 v216, 0x3000, v216
	v_and_b32_e32 v218, 31, v198
	v_lshrrev_b32_e32 v219, 5, v198
	v_lshrrev_b32_e32 v220, 3, v198
	v_and_b32_e32 v221, 7, v198
	v_mul_u32_u24_e32 v222, 0x90, v220
	v_lshl_add_u32 v222, v221, 4, v222
	v_add_u32_e32 v217, v222, v216
	v_mul_u32_u24_e32 v222, 0x90, v218
	v_lshl_add_u32 v222, v219, 3, v222
	v_add_u32_e32 v216, v222, v216
	v_sub_u32_e32 v220, v220, v218
	v_lshlrev_b32_e32 v220, 11, v220
	v_lshl_add_u32 v220, v221, 4, v220
	v_lshlrev_b32_e32 v219, 3, v219
	v_sub_u32_e32 v220, v220, v219
	v_ashrrev_i32_e32 v221, 31, v220
	v_lshl_add_u64 v[218:219], v[8:9], 0, v[220:221]
	ds_write_b64 v216, v[4:5]
	v_and_b32_e32 v3, 0xffff0000, v124
	v_lshlrev_b32_e32 v2, 16, v124
	v_pk_mul_f32 v[4:5], v[36:37], v[6:7] op_sel_hi:[1,0]
	s_nop 0
	v_pk_mul_f32 v[2:3], v[4:5], v[2:3]
	v_and_b32_e32 v5, 0xffff0000, v125
	v_lshlrev_b32_e32 v4, 16, v125
	v_pk_mul_f32 v[4:5], v[10:11], v[4:5]
	v_cvt_pk_bf16_f32 v2, v2, v3
	v_cvt_pk_bf16_f32 v3, v4, v5
	ds_write_b64 v216, v[2:3] offset:16
	v_and_b32_e32 v3, 0xffff0000, v122
	v_lshlrev_b32_e32 v2, 16, v122
	v_pk_mul_f32 v[4:5], v[40:41], v[6:7] op_sel_hi:[1,0]
	v_pk_mul_f32 v[10:11], v[42:43], v[6:7] op_sel_hi:[1,0]
	v_pk_mul_f32 v[2:3], v[4:5], v[2:3]
	v_and_b32_e32 v5, 0xffff0000, v123
	v_lshlrev_b32_e32 v4, 16, v123
	v_pk_mul_f32 v[4:5], v[10:11], v[4:5]
	v_cvt_pk_bf16_f32 v2, v2, v3
	v_cvt_pk_bf16_f32 v3, v4, v5
	ds_write_b64 v216, v[2:3] offset:32
	v_and_b32_e32 v3, 0xffff0000, v120
	v_lshlrev_b32_e32 v2, 16, v120
	v_pk_mul_f32 v[4:5], v[44:45], v[6:7] op_sel_hi:[1,0]
	v_pk_mul_f32 v[10:11], v[46:47], v[6:7] op_sel_hi:[1,0]
	v_pk_mul_f32 v[2:3], v[4:5], v[2:3]
	v_and_b32_e32 v5, 0xffff0000, v121
	v_lshlrev_b32_e32 v4, 16, v121
	v_pk_mul_f32 v[4:5], v[10:11], v[4:5]
	v_cvt_pk_bf16_f32 v2, v2, v3
	v_cvt_pk_bf16_f32 v3, v4, v5
	ds_write_b64 v216, v[2:3] offset:48
	v_and_b32_e32 v3, 0xffff0000, v118
	v_lshlrev_b32_e32 v2, 16, v118
	v_pk_mul_f32 v[4:5], v[16:17], v[6:7] op_sel_hi:[1,0]
	v_pk_mul_f32 v[10:11], v[18:19], v[6:7] op_sel_hi:[1,0]
	v_pk_mul_f32 v[2:3], v[4:5], v[2:3]
	v_and_b32_e32 v5, 0xffff0000, v119
	v_lshlrev_b32_e32 v4, 16, v119
	v_pk_mul_f32 v[4:5], v[10:11], v[4:5]
	v_cvt_pk_bf16_f32 v2, v2, v3
	v_cvt_pk_bf16_f32 v3, v4, v5
	ds_write_b64 v216, v[2:3] offset:64
	v_and_b32_e32 v3, 0xffff0000, v116
	v_lshlrev_b32_e32 v2, 16, v116
	v_pk_mul_f32 v[4:5], v[20:21], v[6:7] op_sel_hi:[1,0]
	v_pk_mul_f32 v[10:11], v[22:23], v[6:7] op_sel_hi:[1,0]
	v_pk_mul_f32 v[2:3], v[4:5], v[2:3]
	v_and_b32_e32 v5, 0xffff0000, v117
	v_lshlrev_b32_e32 v4, 16, v117
	v_pk_mul_f32 v[4:5], v[10:11], v[4:5]
	v_cvt_pk_bf16_f32 v2, v2, v3
	v_cvt_pk_bf16_f32 v3, v4, v5
	ds_write_b64 v216, v[2:3] offset:80
	v_and_b32_e32 v3, 0xffff0000, v114
	v_lshlrev_b32_e32 v2, 16, v114
	v_pk_mul_f32 v[4:5], v[24:25], v[6:7] op_sel_hi:[1,0]
	v_pk_mul_f32 v[10:11], v[26:27], v[6:7] op_sel_hi:[1,0]
	v_pk_mul_f32 v[2:3], v[4:5], v[2:3]
	v_and_b32_e32 v5, 0xffff0000, v115
	v_lshlrev_b32_e32 v4, 16, v115
	v_pk_mul_f32 v[4:5], v[10:11], v[4:5]
	v_cvt_pk_bf16_f32 v2, v2, v3
	v_cvt_pk_bf16_f32 v3, v4, v5
	ds_write_b64 v216, v[2:3] offset:96
	v_and_b32_e32 v3, 0xffff0000, v112
	v_lshlrev_b32_e32 v2, 16, v112
	v_pk_mul_f32 v[4:5], v[28:29], v[6:7] op_sel_hi:[1,0]
	v_pk_mul_f32 v[6:7], v[30:31], v[6:7] op_sel_hi:[1,0]
	v_pk_mul_f32 v[2:3], v[4:5], v[2:3]
	v_and_b32_e32 v5, 0xffff0000, v113
	v_lshlrev_b32_e32 v4, 16, v113
	v_pk_mul_f32 v[4:5], v[6:7], v[4:5]
	v_cvt_pk_bf16_f32 v2, v2, v3
	v_cvt_pk_bf16_f32 v3, v4, v5
	ds_write_b64 v216, v[2:3] offset:112
	s_waitcnt lgkmcnt(0)
	ds_read_b128 v[200:203], v217
	ds_read_b128 v[204:207], v217 offset:1152
	ds_read_b128 v[208:211], v217 offset:2304
	ds_read_b128 v[212:215], v217 offset:3456
	v_mov_b32_e32 v220, 0x4000
	v_mov_b32_e32 v221, 0
	s_waitcnt lgkmcnt(3)
	global_store_dwordx4 v[218:219], v[200:203], off
	v_lshl_add_u64 v[218:219], v[218:219], 0, v[220:221]
	s_waitcnt lgkmcnt(2)
	global_store_dwordx4 v[218:219], v[204:207], off
	v_lshl_add_u64 v[218:219], v[218:219], 0, v[220:221]
	s_waitcnt lgkmcnt(1)
	global_store_dwordx4 v[218:219], v[208:211], off
	v_lshl_add_u64 v[218:219], v[218:219], 0, v[220:221]
	s_waitcnt lgkmcnt(0)
	global_store_dwordx4 v[218:219], v[212:215], off
	s_barrier

.Lat3_m5skip:
	s_or_b64 exec, exec, s[16:17]
	v_and_b32_e32 v10, 0xffffffc0, v2
	v_and_b32_e32 v16, 31, v2
	v_bfe_u32 v17, v2, 5, 1
	v_add_u32_e32 v2, 1, v18
	v_cndmask_b32_e64 v111, v2, 33, s[14:15]
	v_or_b32_e32 v2, v19, v16
	v_ashrrev_i32_e32 v3, 31, v2
	v_lshl_add_u32 v126, v0, 8, v10
	v_lshlrev_b64 v[8:9], 10, v[2:3]
	v_ashrrev_i32_e32 v127, 31, v126
	v_lshlrev_b64 v[2:3], 11, v[2:3]
	v_lshl_add_u64 v[8:9], s[8:9], 0, v[8:9]
	v_lshlrev_b64 v[10:11], 1, v[126:127]
	v_lshl_add_u64 v[130:131], s[88:89], 0, v[2:3]
	v_lshl_add_u64 v[8:9], v[8:9], 0, v[10:11]
	v_lshlrev_b32_e32 v0, 3, v17
	v_lshlrev_b32_e32 v132, 4, v17
	v_mov_b32_e32 v133, v1
	v_lshl_add_u64 v[2:3], v[130:131], 0, v[10:11]
	v_lshl_add_u64 v[8:9], v[8:9], 0, v[132:133]
	v_lshl_add_u64 v[2:3], v[2:3], 0, v[0:1]
	s_mov_b64 s[16:17], 0x12e80400
	global_load_dwordx4 v[80:83], v[8:9], off
	global_load_dwordx4 v[84:87], v[8:9], off offset:32
	global_load_dwordx4 v[88:91], v[8:9], off offset:64
	global_load_dwordx4 v[92:95], v[8:9], off offset:96
	v_lshl_add_u64 v[8:9], v[2:3], 0, s[16:17]
	s_mov_b32 s16, 0x12e80000
	v_add_co_u32_e32 v2, vcc, s16, v2
	v_mov_b32_e32 v109, v1
	s_nop 0
	v_addc_co_u32_e32 v3, vcc, 0, v3, vcc
	v_and_b32_e32 v216, 31, v198
	v_lshrrev_b32_e32 v217, 5, v198
	v_lshlrev_b32_e32 v217, 3, v217
	v_lshrrev_b32_e32 v218, 3, v198
	v_and_b32_e32 v219, 7, v198
	v_sub_u32_e32 v220, v218, v216
	v_lshlrev_b32_e32 v220, 11, v220
	v_lshl_add_u32 v220, v219, 4, v220
	v_sub_u32_e32 v220, v220, v217
	v_ashrrev_i32_e32 v221, 31, v220
	v_lshl_add_u64 v[222:223], v[8:9], 0, v[220:221]
	v_lshrrev_b32_e32 v218, 4, v198
	v_and_b32_e32 v219, 15, v198
	v_sub_u32_e32 v220, v218, v216
	v_add_u32_e32 v220, 24, v220
	v_lshlrev_b32_e32 v220, 11, v220
	v_lshl_add_u32 v220, v219, 3, v220
	v_sub_u32_e32 v220, v220, v217
	v_ashrrev_i32_e32 v221, 31, v220
	v_lshl_add_u64 v[218:219], v[8:9], 0, v[220:221]
	v_mov_b32_e32 v220, 0x4000
	v_mov_b32_e32 v221, 0
	global_load_dwordx4 v[112:115], v[222:223], off
	v_lshl_add_u64 v[222:223], v[222:223], 0, v[220:221]
	global_load_dwordx4 v[116:119], v[222:223], off
	v_lshl_add_u64 v[222:223], v[222:223], 0, v[220:221]
	global_load_dwordx4 v[120:123], v[222:223], off
	v_mov_b32_e32 v220, 0x2000
	global_load_dwordx2 v[124:125], v[218:219], off
	v_lshl_add_u64 v[218:219], v[218:219], 0, v[220:221]
	global_load_dwordx2 v[128:129], v[218:219], off
	v_lshl_add_u64 v[2:3], v[4:5], 0, v[106:107]
	v_lshl_add_u64 v[2:3], v[2:3], 0, v[108:109]
	v_cndmask_b32_e64 v0, v145, v151, s[14:15]
	v_cmp_lt_u32_e32 vcc, 1, v111
	global_load_dwordx4 v[8:11], v[2:3], off
	v_mad_i64_i32 v[2:3], s[14:15], v0, v104, 0
	v_cndmask_b32_e64 v0, 0, 64, vcc
	v_lshl_add_u64 v[2:3], v[2:3], 1, v[6:7]
	v_add_u32_e32 v6, v0, v104
	v_ashrrev_i32_e32 v7, 31, v6
	v_lshlrev_b64 v[6:7], 7, v[6:7]
	v_add_u32_e32 v133, -1, v111
	v_lshl_add_u64 v[6:7], v[4:5], 0, v[6:7]
	v_min_u32_e32 v18, 2, v133
	v_lshl_add_u64 v[6:7], v[6:7], 0, v[108:109]
	v_lshlrev_b32_e32 v0, 1, v0
	global_load_dwordx4 v[48:51], v[6:7], off
	v_lshl_add_u64 v[6:7], v[2:3], 0, v[0:1]
	v_lshlrev_b32_e32 v0, 7, v18
	v_lshl_add_u64 v[134:135], v[2:3], 0, v[108:109]
	v_lshl_add_u64 v[2:3], v[2:3], 0, v[0:1]
	v_lshl_add_u64 v[6:7], v[6:7], 0, v[108:109]
	v_lshl_add_u64 v[2:3], v[2:3], 0, v[108:109]
	global_load_dwordx4 v[52:55], v[6:7], off
	global_load_dwordx4 v[100:103], v[2:3], off
	v_lshl_add_u32 v6, v18, 6, v104
	v_ashrrev_i32_e32 v7, 31, v6
	v_lshlrev_b64 v[6:7], 7, v[6:7]
	global_load_dwordx4 v[12:15], v[134:135], off
	v_lshl_add_u64 v[6:7], v[4:5], 0, v[6:7]
	v_lshl_add_u64 v[6:7], v[6:7], 0, v[108:109]
	global_load_dwordx4 v[96:99], v[6:7], off
	s_waitcnt vmcnt(15)
	s_movk_i32 s16, 0x420
	v_cmp_gt_i32_e32 vcc, s16, v211
	s_and_saveexec_b64 s[16:17], vcc
	ds_write_b64 v210, v[208:209]
	s_or_b64 exec, exec, s[16:17]
	s_movk_i32 s16, 0x320
	v_cmp_gt_i32_e32 vcc, s16, v211
	s_and_saveexec_b64 s[16:17], vcc
	ds_write_b64 v210, v[200:201] offset:2048
	s_or_b64 exec, exec, s[16:17]
	s_movk_i32 s16, 0x220
	v_cmp_gt_i32_e32 vcc, s16, v211
	s_and_saveexec_b64 s[16:17], vcc
	ds_write_b64 v210, v[202:203] offset:4096
	s_or_b64 exec, exec, s[16:17]
	s_movk_i32 s16, 0x120
	v_cmp_gt_i32_e32 vcc, s16, v211
	s_and_saveexec_b64 s[16:17], vcc
	ds_write_b64 v210, v[204:205] offset:6144
	s_or_b64 exec, exec, s[16:17]
	v_cmp_gt_i32_e32 vcc, 32, v211
	s_and_saveexec_b64 s[16:17], vcc
	ds_write_b64 v210, v[206:207] offset:8192
	s_or_b64 exec, exec, s[16:17]
	v_mov_b32_e32 v2, v1
	v_mov_b32_e32 v3, v1
	v_lshlrev_b32_e32 v136, 2, v17
	v_lshl_add_u64 v[138:139], v[4:5], 0, v[108:109]
	v_mul_u32_u24_e32 v109, 0x90, v16
	v_mad_u32_u24 v152, v16, s43, v141
	v_mov_b32_e32 v0, v1
	v_mov_b32_e32 v4, v1
	v_mov_b32_e32 v5, v1
	v_mov_b32_e32 v6, v1
	v_mov_b32_e32 v7, v1
	s_mov_b32 s19, 0
	v_mov_b32_e32 v154, 0xf149f2ca
	v_mov_b32_e32 v153, 0
	s_mov_b64 s[14:15], 0
	s_waitcnt vmcnt(5)
	ds_write_b128 v105, v[8:11]
	s_waitcnt vmcnt(1)
	ds_write_b128 v143, v[12:15]
	v_mov_b32_e32 v14, v1
	v_mov_b32_e32 v15, v1
	v_mov_b32_e32 v8, v1
	v_mov_b32_e32 v9, v1
	v_mov_b32_e32 v10, v1
	v_mov_b32_e32 v11, v1
	v_mov_b32_e32 v12, v1
	v_mov_b32_e32 v13, v1
	v_mov_b64_e32 v[30:31], v[14:15]
	v_mov_b64_e32 v[46:47], v[14:15]
	v_mov_b64_e32 v[28:29], v[12:13]
	v_mov_b64_e32 v[26:27], v[10:11]
	v_mov_b64_e32 v[24:25], v[8:9]
	v_mov_b64_e32 v[22:23], v[6:7]
	v_mov_b64_e32 v[20:21], v[4:5]
	v_mov_b64_e32 v[18:19], v[2:3]
	v_mov_b64_e32 v[16:17], v[0:1]
	v_mov_b64_e32 v[44:45], v[12:13]
	v_mov_b64_e32 v[42:43], v[10:11]
	v_mov_b64_e32 v[40:41], v[8:9]
	v_mov_b64_e32 v[38:39], v[6:7]
	v_mov_b64_e32 v[36:37], v[4:5]
	v_mov_b64_e32 v[34:35], v[2:3]
	v_mov_b64_e32 v[32:33], v[0:1]
	s_waitcnt lgkmcnt(0)
	s_barrier
	s_branch .LBB0_803
